# x13 + F2 K-loop k-inner MFMA order (non-shifting accumulators)
# speedup vs baseline: 1.0031x; 1.0010x over previous
; #define PG8_STAGE(bufoff, gbase, voff) do { _Pragma("unroll") for (int _i = 0; _i < 2; ++_i) \
;         __builtin_amdgcn_global_load_lds((const unsigned*)((const char*)(gbase) + (voff)[_i]), (PG8_LAS unsigned*)(lds + (bufoff) + ldsw + _i * 8192), 16, 0, 0); } while (0)
; #define PG8_LDA(dst, b, h) do { _Pragma("unroll") for (int m = 0; m < 4; ++m) _Pragma("unroll") for (int k = 0; k < 2; ++k) dst[m][k] = *(const PG8_LAS bf16x8*)(lds + PG8_SA(b, h) + aoff + m * 2048 + k * 1024); } while (0)
; #define PG8_WAIT_V(n) asm volatile("s_waitcnt vmcnt(" #n ")" ::: "memory")
; #define PG8_WAIT_L(n) asm volatile("s_waitcnt lgkmcnt(" #n ")" ::: "memory")
; #define PG8_BAR __builtin_amdgcn_s_barrier()
; template <class Epi, class Sched, bool ALIGN_EPI = true, bool SP2 = true>
; __device__ __forceinline__ void gemm_phase(PG8_LAS unsigned char* lds, const Gemm g, const Sched& S, const Epi& E, const int tid) {
;     ...
;         for (int t = 0; t < nt; t += 2) {
;             const bool last = (t == nt - 2);
;             const char* a1 = cA + (size_t)(t + 1) * kstep;
;             const char* a2 = last ? nA : cA + (size_t)(t + 2) * kstep; const char* b2 = last ? nB : cB + (size_t)(t + 2) * kstep;
;             const char* a3 = a2 + kstep; const char* b3 = b2 + kstep;
;             if (last && has_next) S.a_ready(nxt);
;             if constexpr (SP2) {
;             PG8_LDB(B0, 0, 0); PG8_LDB(B1, 0, 1); PG8_SCHED; PG8_LDA(At, 0, 0); PG8_STAGE(PG8_SA(1, 1), a1 + hstepA, voffA);
;             PG8_WAIT_V(8); PG8_WAIT_L(0); PG8_BAR; PG8_MMA(0, 0, At, B0); PG8_MMA(0, 1, At, B1); PG8_BAR; PG8_SCHED;
;             PG8_LDA(At, 0, 1); PG8_STAGE(PG8_SB(0, 0), b2, voffB); PG8_STAGE(PG8_SB(0, 1), b2 + hstepB, voffB); PG8_STAGE(PG8_SA(0, 0), a2, voffA);
;             PG8_WAIT_V(8); PG8_WAIT_L(0); PG8_BAR; PG8_MMA(1, 0, At, B0); PG8_MMA(1, 1, At, B1); PG8_BAR; PG8_SCHED;
;             PG8_LDB(B0, 1, 0); PG8_LDB(B1, 1, 1); PG8_SCHED; PG8_LDA(At, 1, 0); PG8_STAGE(PG8_SA(0, 1), a2 + hstepA, voffA);
;             PG8_WAIT_V(8); PG8_WAIT_L(0); PG8_BAR; PG8_MMA(0, 0, At, B0); PG8_MMA(0, 1, At, B1); PG8_BAR; PG8_SCHED;
;             PG8_LDA(At, 1, 1); PG8_STAGE(PG8_SB(1, 0), b3, voffB); PG8_STAGE(PG8_SB(1, 1), b3 + hstepB, voffB); PG8_STAGE(PG8_SA(1, 0), a3, voffA);
;             PG8_WAIT_V(8); PG8_WAIT_L(0); PG8_BAR; PG8_MMA(1, 0, At, B0); PG8_MMA(1, 1, At, B1); PG8_BAR; PG8_SCHED;
.LBB0_1523:
	s_add_i32 vcc_lo, s72, 2
	s_add_u32 s70, s82, 0x100
	s_addc_u32 s71, s83, 0
	s_add_i32 s30, 0, 0x10000
	s_cmp_eq_u32 s29, s72
	s_cselect_b32 s81, s63, s71
	s_cselect_b32 s80, s62, s70
	v_add_u32_e32 v96, s30, v141
	s_cselect_b32 s73, s65, s59
	s_cselect_b32 s72, s64, s57
	s_add_i32 s31, 0, 0x14000
	ds_read_b128 v[146:149], v96
	ds_read_b128 v[150:153], v96 offset:1024
	ds_read_b128 v[154:157], v96 offset:2048
	ds_read_b128 v[158:161], v96 offset:3072
	v_add_u32_e32 v96, s31, v141
	ds_read_b128 v[162:165], v96
	ds_read_b128 v[166:169], v96 offset:1024
	ds_read_b128 v[170:173], v96 offset:2048
	ds_read_b128 v[174:177], v96 offset:3072
	v_lshl_add_u64 v[98:99], s[82:83], 0, v[136:137]
	s_add_i32 m0, s23, 0xc000
	ds_read_b128 v[178:181], v145
	ds_read_b128 v[182:185], v145 offset:1024
	ds_read_b128 v[186:189], v145 offset:2048
	ds_read_b128 v[190:193], v145 offset:3072
	ds_read_b128 v[194:197], v145 offset:4096
	ds_read_b128 v[200:203], v145 offset:5120
	ds_read_b128 v[206:209], v145 offset:6144
	ds_read_b128 v[210:213], v145 offset:7168
	global_load_lds_dwordx4 v[98:99], off
	v_lshl_add_u64 v[98:99], s[82:83], 0, v[138:139]
	s_add_i32 m0, s23, 0xe000
	s_nop 0
	global_load_lds_dwordx4 v[98:99], off
	s_waitcnt vmcnt(8)
	s_waitcnt lgkmcnt(0)
	s_barrier
	s_setprio 1
	s_waitcnt lgkmcnt(0)
	v_mfma_f32_16x16x32_bf16 v[52:55], v[146:149], v[178:181], v[52:55]
	v_mfma_f32_16x16x32_bf16 v[52:55], v[150:153], v[182:185], v[52:55]
	v_mfma_f32_16x16x32_bf16 v[56:59], v[154:157], v[178:181], v[56:59]
	v_mfma_f32_16x16x32_bf16 v[56:59], v[158:161], v[182:185], v[56:59]
	v_mfma_f32_16x16x32_bf16 v[104:107], v[146:149], v[186:189], v[104:107]
	v_mfma_f32_16x16x32_bf16 v[104:107], v[150:153], v[190:193], v[104:107]
	v_mfma_f32_16x16x32_bf16 v[84:87], v[154:157], v[186:189], v[84:87]
	v_mfma_f32_16x16x32_bf16 v[84:87], v[158:161], v[190:193], v[84:87]
	v_mfma_f32_16x16x32_bf16 v[110:113], v[146:149], v[194:197], v[110:113]
	v_mfma_f32_16x16x32_bf16 v[110:113], v[150:153], v[200:203], v[110:113]
	v_mfma_f32_16x16x32_bf16 v[98:101], v[154:157], v[194:197], v[100:103]
	v_mfma_f32_16x16x32_bf16 v[88:91], v[146:149], v[206:209], v[88:91]
	v_mfma_f32_16x16x32_bf16 v[88:91], v[150:153], v[210:213], v[88:91]
	v_mfma_f32_16x16x32_bf16 v[80:83], v[154:157], v[206:209], v[80:83]
	v_mfma_f32_16x16x32_bf16 v[80:83], v[158:161], v[210:213], v[80:83]
	v_mfma_f32_16x16x32_bf16 v[98:101], v[158:161], v[200:203], v[98:101]
	s_setprio 0
	s_setprio 1
	v_mfma_f32_16x16x32_bf16 v[48:51], v[162:165], v[178:181], v[48:51]
	v_mfma_f32_16x16x32_bf16 v[48:51], v[166:169], v[182:185], v[48:51]
	v_mfma_f32_16x16x32_bf16 v[44:47], v[170:173], v[178:181], v[44:47]
	v_mfma_f32_16x16x32_bf16 v[44:47], v[174:177], v[182:185], v[44:47]
	v_mfma_f32_16x16x32_bf16 v[76:79], v[162:165], v[186:189], v[76:79]
	v_mfma_f32_16x16x32_bf16 v[76:79], v[166:169], v[190:193], v[76:79]
	v_mfma_f32_16x16x32_bf16 v[68:71], v[170:173], v[186:189], v[68:71]
	v_mfma_f32_16x16x32_bf16 v[68:71], v[174:177], v[190:193], v[68:71]
	v_mfma_f32_16x16x32_bf16 v[130:133], v[162:165], v[194:197], v[130:133]
	v_mfma_f32_16x16x32_bf16 v[130:133], v[166:169], v[200:203], v[130:133]
	v_mfma_f32_16x16x32_bf16 v[92:95], v[170:173], v[194:197], v[92:95]
	v_mfma_f32_16x16x32_bf16 v[92:95], v[174:177], v[200:203], v[92:95]
	v_mfma_f32_16x16x32_bf16 v[72:75], v[162:165], v[206:209], v[72:75]
	v_mfma_f32_16x16x32_bf16 v[64:67], v[170:173], v[206:209], v[64:67]
	s_setprio 2
	s_barrier
	v_mfma_f32_16x16x32_bf16 v[72:75], v[166:169], v[210:213], v[72:75]
	v_mfma_f32_16x16x32_bf16 v[64:67], v[174:177], v[210:213], v[64:67]
	s_setprio 0
	s_add_i32 s30, s30, s22
	v_lshl_add_u64 v[224:225], s[72:73], 0, v[108:109]
	s_mov_b32 m0, s30
	ds_read_b128 v[178:181], v145 offset:16384
	ds_read_b128 v[182:185], v145 offset:17408
	ds_read_b128 v[186:189], v145 offset:18432
	ds_read_b128 v[190:193], v145 offset:19456
	ds_read_b128 v[194:197], v145 offset:20480
	ds_read_b128 v[200:203], v145 offset:21504
	ds_read_b128 v[206:209], v145 offset:22528
	ds_read_b128 v[210:213], v145 offset:23552
	global_load_lds_dwordx4 v[224:225], off
	s_add_i32 m0, s30, 0x2000
	s_add_u32 s82, s72, 0x160000
	v_lshl_add_u64 v[226:227], s[72:73], 0, v[134:135]
	s_addc_u32 s83, s73, 0
	s_add_i32 s30, s31, s22
	global_load_lds_dwordx4 v[226:227], off
	v_lshl_add_u64 v[102:103], s[82:83], 0, v[108:109]
	s_mov_b32 m0, s30
	v_lshl_add_u64 v[228:229], s[80:81], 0, v[108:109]
	global_load_lds_dwordx4 v[102:103], off
	v_lshl_add_u64 v[102:103], s[82:83], 0, v[134:135]
	s_add_i32 m0, s30, 0x2000
	v_lshl_add_u64 v[230:231], s[80:81], 0, v[134:135]
	global_load_lds_dwordx4 v[102:103], off
	s_mov_b32 m0, s23
	s_nop 0
	global_load_lds_dwordx4 v[228:229], off
	s_mov_b32 m0, s24
	s_nop 0
	global_load_lds_dwordx4 v[230:231], off
	s_waitcnt vmcnt(8)
	s_waitcnt lgkmcnt(0)
	s_barrier
; #define PG8_STAGE(bufoff, gbase, voff) do { _Pragma("unroll") for (int _i = 0; _i < 2; ++_i) \
;         __builtin_amdgcn_global_load_lds((const unsigned*)((const char*)(gbase) + (voff)[_i]), (PG8_LAS unsigned*)(lds + (bufoff) + ldsw + _i * 8192), 16, 0, 0); } while (0)
; #define PG8_LDA(dst, b, h) do { _Pragma("unroll") for (int m = 0; m < 4; ++m) _Pragma("unroll") for (int k = 0; k < 2; ++k) dst[m][k] = *(const PG8_LAS bf16x8*)(lds + PG8_SA(b, h) + aoff + m * 2048 + k * 1024); } while (0)
; #define PG8_WAIT_V(n) asm volatile("s_waitcnt vmcnt(" #n ")" ::: "memory")
; #define PG8_WAIT_L(n) asm volatile("s_waitcnt lgkmcnt(" #n ")" ::: "memory")
; #define PG8_BAR __builtin_amdgcn_s_barrier()
; template <class Epi, class Sched, bool ALIGN_EPI = true, bool SP2 = true>
; __device__ __forceinline__ void gemm_phase(PG8_LAS unsigned char* lds, const Gemm g, const Sched& S, const Epi& E, const int tid) {
;     ...
;         for (int t = 0; t < nt; t += 2) {
;             const bool last = (t == nt - 2);
;             const char* a1 = cA + (size_t)(t + 1) * kstep;
;             const char* a2 = last ? nA : cA + (size_t)(t + 2) * kstep; const char* b2 = last ? nB : cB + (size_t)(t + 2) * kstep;
;             const char* a3 = a2 + kstep; const char* b3 = b2 + kstep;
;             if (last && has_next) S.a_ready(nxt);
;             if constexpr (SP2) {
;             PG8_LDB(B0, 0, 0); PG8_LDB(B1, 0, 1); PG8_SCHED; PG8_LDA(At, 0, 0); PG8_STAGE(PG8_SA(1, 1), a1 + hstepA, voffA);
;             PG8_WAIT_V(8); PG8_WAIT_L(0); PG8_BAR; PG8_MMA(0, 0, At, B0); PG8_MMA(0, 1, At, B1); PG8_BAR; PG8_SCHED;
;             PG8_LDA(At, 0, 1); PG8_STAGE(PG8_SB(0, 0), b2, voffB); PG8_STAGE(PG8_SB(0, 1), b2 + hstepB, voffB); PG8_STAGE(PG8_SA(0, 0), a2, voffA);
;             PG8_WAIT_V(8); PG8_WAIT_L(0); PG8_BAR; PG8_MMA(1, 0, At, B0); PG8_MMA(1, 1, At, B1); PG8_BAR; PG8_SCHED;
;             PG8_LDB(B0, 1, 0); PG8_LDB(B1, 1, 1); PG8_SCHED; PG8_LDA(At, 1, 0); PG8_STAGE(PG8_SA(0, 1), a2 + hstepA, voffA);
;             PG8_WAIT_V(8); PG8_WAIT_L(0); PG8_BAR; PG8_MMA(0, 0, At, B0); PG8_MMA(0, 1, At, B1); PG8_BAR; PG8_SCHED;
;             PG8_LDA(At, 1, 1); PG8_STAGE(PG8_SB(1, 0), b3, voffB); PG8_STAGE(PG8_SB(1, 1), b3 + hstepB, voffB); PG8_STAGE(PG8_SA(1, 0), a3, voffA);
;             PG8_WAIT_V(8); PG8_WAIT_L(0); PG8_BAR; PG8_MMA(1, 0, At, B0); PG8_MMA(1, 1, At, B1); PG8_BAR; PG8_SCHED;
	s_setprio 1
	s_waitcnt lgkmcnt(0)
	v_mfma_f32_16x16x32_bf16 v[126:129], v[146:149], v[178:181], v[126:129]
	v_mfma_f32_16x16x32_bf16 v[126:129], v[150:153], v[182:185], v[126:129]
	v_mfma_f32_16x16x32_bf16 v[122:125], v[154:157], v[178:181], v[122:125]
	v_mfma_f32_16x16x32_bf16 v[122:125], v[158:161], v[182:185], v[122:125]
	v_mfma_f32_16x16x32_bf16 v[60:63], v[146:149], v[186:189], v[60:63]
	v_mfma_f32_16x16x32_bf16 v[60:63], v[150:153], v[190:193], v[60:63]
	v_mfma_f32_16x16x32_bf16 v[40:43], v[154:157], v[186:189], v[40:43]
	v_mfma_f32_16x16x32_bf16 v[40:43], v[158:161], v[190:193], v[40:43]
	v_mfma_f32_16x16x32_bf16 v[28:31], v[146:149], v[194:197], v[28:31]
	v_mfma_f32_16x16x32_bf16 v[28:31], v[150:153], v[200:203], v[28:31]
	v_mfma_f32_16x16x32_bf16 v[24:27], v[154:157], v[194:197], v[24:27]
	v_mfma_f32_16x16x32_bf16 v[24:27], v[158:161], v[200:203], v[24:27]
	v_mfma_f32_16x16x32_bf16 v[12:15], v[146:149], v[206:209], v[12:15]
	v_mfma_f32_16x16x32_bf16 v[12:15], v[150:153], v[210:213], v[12:15]
	v_mfma_f32_16x16x32_bf16 v[8:11], v[154:157], v[206:209], v[8:11]
	v_mfma_f32_16x16x32_bf16 v[8:11], v[158:161], v[210:213], v[8:11]
	s_setprio 0
	s_setprio 1
	v_mfma_f32_16x16x32_bf16 v[118:121], v[162:165], v[178:181], v[118:121]
	v_mfma_f32_16x16x32_bf16 v[118:121], v[166:169], v[182:185], v[118:121]
	v_mfma_f32_16x16x32_bf16 v[114:117], v[170:173], v[178:181], v[114:117]
	v_mfma_f32_16x16x32_bf16 v[114:117], v[174:177], v[182:185], v[114:117]
	v_mfma_f32_16x16x32_bf16 v[36:39], v[162:165], v[186:189], v[36:39]
	v_mfma_f32_16x16x32_bf16 v[36:39], v[166:169], v[190:193], v[36:39]
	v_mfma_f32_16x16x32_bf16 v[32:35], v[170:173], v[186:189], v[32:35]
	v_mfma_f32_16x16x32_bf16 v[32:35], v[174:177], v[190:193], v[32:35]
	v_mfma_f32_16x16x32_bf16 v[20:23], v[162:165], v[194:197], v[20:23]
	v_mfma_f32_16x16x32_bf16 v[20:23], v[166:169], v[200:203], v[20:23]
	v_mfma_f32_16x16x32_bf16 v[16:19], v[170:173], v[194:197], v[16:19]
	v_mfma_f32_16x16x32_bf16 v[16:19], v[174:177], v[200:203], v[16:19]
	v_mfma_f32_16x16x32_bf16 v[4:7], v[162:165], v[206:209], v[4:7]
	v_mfma_f32_16x16x32_bf16 v[0:3], v[170:173], v[206:209], v[0:3]
	s_setprio 2
	s_barrier
	v_mfma_f32_16x16x32_bf16 v[4:7], v[166:169], v[210:213], v[4:7]
	v_mfma_f32_16x16x32_bf16 v[0:3], v[174:177], v[210:213], v[0:3]
	s_setprio 0
	s_add_i32 s30, 0, 0x18000
	v_add_u32_e32 v96, s30, v141
	s_add_i32 s31, 0, 0x1c000
	ds_read_b128 v[146:149], v96
	ds_read_b128 v[150:153], v96 offset:1024
	ds_read_b128 v[154:157], v96 offset:2048
	ds_read_b128 v[158:161], v96 offset:3072
	v_add_u32_e32 v96, s31, v141
	ds_read_b128 v[162:165], v96
	ds_read_b128 v[166:169], v96 offset:1024
	ds_read_b128 v[170:173], v96 offset:2048
	ds_read_b128 v[174:177], v96 offset:3072
	s_add_u32 s80, s80, 0x160000
	s_addc_u32 s81, s81, 0
	s_mov_b32 m0, s25
	v_lshl_add_u64 v[102:103], s[80:81], 0, v[108:109]
	ds_read_b128 v[178:181], v145 offset:32768
	ds_read_b128 v[182:185], v145 offset:33792
	ds_read_b128 v[186:189], v145 offset:34816
	ds_read_b128 v[190:193], v145 offset:35840
	ds_read_b128 v[194:197], v145 offset:36864
	ds_read_b128 v[200:203], v145 offset:37888
	ds_read_b128 v[206:209], v145 offset:38912
	ds_read_b128 v[210:213], v145 offset:39936
	global_load_lds_dwordx4 v[102:103], off
	v_lshl_add_u64 v[102:103], s[80:81], 0, v[134:135]
	s_mov_b32 m0, s49
	s_nop 0
	global_load_lds_dwordx4 v[102:103], off
	s_waitcnt vmcnt(8)
	s_waitcnt lgkmcnt(0)
	s_barrier
	s_setprio 1
	s_waitcnt lgkmcnt(0)
	v_mfma_f32_16x16x32_bf16 v[52:55], v[146:149], v[178:181], v[52:55]
	v_mfma_f32_16x16x32_bf16 v[52:55], v[150:153], v[182:185], v[52:55]
	v_mfma_f32_16x16x32_bf16 v[56:59], v[154:157], v[178:181], v[56:59]
	v_mfma_f32_16x16x32_bf16 v[56:59], v[158:161], v[182:185], v[56:59]
	v_mfma_f32_16x16x32_bf16 v[102:105], v[146:149], v[186:189], v[104:107]
	v_mfma_f32_16x16x32_bf16 v[84:87], v[154:157], v[186:189], v[84:87]
	v_mfma_f32_16x16x32_bf16 v[84:87], v[158:161], v[190:193], v[84:87]
	v_mfma_f32_16x16x32_bf16 v[110:113], v[146:149], v[194:197], v[110:113]
	v_mfma_f32_16x16x32_bf16 v[110:113], v[150:153], v[200:203], v[110:113]
	v_mfma_f32_16x16x32_bf16 v[98:101], v[154:157], v[194:197], v[98:101]
	v_mfma_f32_16x16x32_bf16 v[88:91], v[146:149], v[206:209], v[88:91]
	v_mfma_f32_16x16x32_bf16 v[88:91], v[150:153], v[210:213], v[88:91]
	v_mfma_f32_16x16x32_bf16 v[80:83], v[154:157], v[206:209], v[80:83]
	v_mfma_f32_16x16x32_bf16 v[80:83], v[158:161], v[210:213], v[80:83]
	v_mfma_f32_16x16x32_bf16 v[104:107], v[150:153], v[190:193], v[102:105]
	v_mfma_f32_16x16x32_bf16 v[100:103], v[158:161], v[200:203], v[98:101]
	s_setprio 0
	s_setprio 1
	v_mfma_f32_16x16x32_bf16 v[48:51], v[162:165], v[178:181], v[48:51]
	v_mfma_f32_16x16x32_bf16 v[48:51], v[166:169], v[182:185], v[48:51]
	v_mfma_f32_16x16x32_bf16 v[44:47], v[170:173], v[178:181], v[44:47]
	v_mfma_f32_16x16x32_bf16 v[44:47], v[174:177], v[182:185], v[44:47]
	v_mfma_f32_16x16x32_bf16 v[76:79], v[162:165], v[186:189], v[76:79]
	v_mfma_f32_16x16x32_bf16 v[76:79], v[166:169], v[190:193], v[76:79]
	v_mfma_f32_16x16x32_bf16 v[68:71], v[170:173], v[186:189], v[68:71]
	v_mfma_f32_16x16x32_bf16 v[68:71], v[174:177], v[190:193], v[68:71]
	v_mfma_f32_16x16x32_bf16 v[130:133], v[162:165], v[194:197], v[130:133]
	v_mfma_f32_16x16x32_bf16 v[130:133], v[166:169], v[200:203], v[130:133]
	v_mfma_f32_16x16x32_bf16 v[92:95], v[170:173], v[194:197], v[92:95]
	v_mfma_f32_16x16x32_bf16 v[92:95], v[174:177], v[200:203], v[92:95]
	v_mfma_f32_16x16x32_bf16 v[72:75], v[162:165], v[206:209], v[72:75]
	v_mfma_f32_16x16x32_bf16 v[64:67], v[170:173], v[206:209], v[64:67]
	s_setprio 2
	s_barrier
; #define PG8_STAGE(bufoff, gbase, voff) do { _Pragma("unroll") for (int _i = 0; _i < 2; ++_i) \
;         __builtin_amdgcn_global_load_lds((const unsigned*)((const char*)(gbase) + (voff)[_i]), (PG8_LAS unsigned*)(lds + (bufoff) + ldsw + _i * 8192), 16, 0, 0); } while (0)
; #define PG8_LDA(dst, b, h) do { _Pragma("unroll") for (int m = 0; m < 4; ++m) _Pragma("unroll") for (int k = 0; k < 2; ++k) dst[m][k] = *(const PG8_LAS bf16x8*)(lds + PG8_SA(b, h) + aoff + m * 2048 + k * 1024); } while (0)
; #define PG8_WAIT_V(n) asm volatile("s_waitcnt vmcnt(" #n ")" ::: "memory")
; #define PG8_WAIT_L(n) asm volatile("s_waitcnt lgkmcnt(" #n ")" ::: "memory")
; #define PG8_BAR __builtin_amdgcn_s_barrier()
; template <class Epi, class Sched, bool ALIGN_EPI = true, bool SP2 = true>
; __device__ __forceinline__ void gemm_phase(PG8_LAS unsigned char* lds, const Gemm g, const Sched& S, const Epi& E, const int tid) {
;     ...
;         for (int t = 0; t < nt; t += 2) {
;             const bool last = (t == nt - 2);
;             const char* a1 = cA + (size_t)(t + 1) * kstep;
;             const char* a2 = last ? nA : cA + (size_t)(t + 2) * kstep; const char* b2 = last ? nB : cB + (size_t)(t + 2) * kstep;
;             const char* a3 = a2 + kstep; const char* b3 = b2 + kstep;
;             if (last && has_next) S.a_ready(nxt);
;             if constexpr (SP2) {
;             PG8_LDB(B0, 0, 0); PG8_LDB(B1, 0, 1); PG8_SCHED; PG8_LDA(At, 0, 0); PG8_STAGE(PG8_SA(1, 1), a1 + hstepA, voffA);
;             PG8_WAIT_V(8); PG8_WAIT_L(0); PG8_BAR; PG8_MMA(0, 0, At, B0); PG8_MMA(0, 1, At, B1); PG8_BAR; PG8_SCHED;
;             PG8_LDA(At, 0, 1); PG8_STAGE(PG8_SB(0, 0), b2, voffB); PG8_STAGE(PG8_SB(0, 1), b2 + hstepB, voffB); PG8_STAGE(PG8_SA(0, 0), a2, voffA);
;             PG8_WAIT_V(8); PG8_WAIT_L(0); PG8_BAR; PG8_MMA(1, 0, At, B0); PG8_MMA(1, 1, At, B1); PG8_BAR; PG8_SCHED;
;             PG8_LDB(B0, 1, 0); PG8_LDB(B1, 1, 1); PG8_SCHED; PG8_LDA(At, 1, 0); PG8_STAGE(PG8_SA(0, 1), a2 + hstepA, voffA);
;             PG8_WAIT_V(8); PG8_WAIT_L(0); PG8_BAR; PG8_MMA(0, 0, At, B0); PG8_MMA(0, 1, At, B1); PG8_BAR; PG8_SCHED;
;             PG8_LDA(At, 1, 1); PG8_STAGE(PG8_SB(1, 0), b3, voffB); PG8_STAGE(PG8_SB(1, 1), b3 + hstepB, voffB); PG8_STAGE(PG8_SA(1, 0), a3, voffA);
;             PG8_WAIT_V(8); PG8_WAIT_L(0); PG8_BAR; PG8_MMA(1, 0, At, B0); PG8_MMA(1, 1, At, B1); PG8_BAR; PG8_SCHED;
	v_mfma_f32_16x16x32_bf16 v[72:75], v[166:169], v[210:213], v[72:75]
	v_mfma_f32_16x16x32_bf16 v[64:67], v[174:177], v[210:213], v[64:67]
	s_setprio 0
	s_add_i32 s30, s30, s22
	v_lshl_add_u64 v[98:99], v[224:225], 0, s[4:5]
	s_mov_b32 m0, s30
	ds_read_b128 v[178:181], v145 offset:49152
	ds_read_b128 v[182:185], v145 offset:50176
	ds_read_b128 v[186:189], v145 offset:51200
	ds_read_b128 v[190:193], v145 offset:52224
	ds_read_b128 v[194:197], v145 offset:53248
	ds_read_b128 v[200:203], v145 offset:54272
	ds_read_b128 v[206:209], v145 offset:55296
	ds_read_b128 v[210:213], v145 offset:56320
	global_load_lds_dwordx4 v[98:99], off
	s_add_i32 m0, s30, 0x2000
	s_add_u32 s72, s72, 0x160080
	v_lshl_add_u64 v[98:99], v[226:227], 0, s[4:5]
	s_addc_u32 s73, s73, 0
	s_add_i32 s30, s31, s22
	global_load_lds_dwordx4 v[98:99], off
	v_lshl_add_u64 v[98:99], s[72:73], 0, v[108:109]
	s_mov_b32 m0, s30
	s_nop 0
	global_load_lds_dwordx4 v[98:99], off
	v_lshl_add_u64 v[98:99], s[72:73], 0, v[134:135]
	s_add_i32 m0, s30, 0x2000
	s_nop 0
	global_load_lds_dwordx4 v[98:99], off
	v_lshl_add_u64 v[98:99], v[228:229], 0, s[4:5]
	s_mov_b32 m0, s91
	s_nop 0
	global_load_lds_dwordx4 v[98:99], off
	v_lshl_add_u64 v[98:99], v[230:231], 0, s[4:5]
	s_mov_b32 m0, s86
	s_nop 0
	global_load_lds_dwordx4 v[98:99], off
	s_waitcnt vmcnt(8)
	s_waitcnt lgkmcnt(0)
	s_barrier
	s_setprio 1
	s_waitcnt lgkmcnt(0)
	v_mfma_f32_16x16x32_bf16 v[126:129], v[146:149], v[178:181], v[126:129]
	v_mfma_f32_16x16x32_bf16 v[126:129], v[150:153], v[182:185], v[126:129]
	v_mfma_f32_16x16x32_bf16 v[122:125], v[154:157], v[178:181], v[122:125]
	v_mfma_f32_16x16x32_bf16 v[122:125], v[158:161], v[182:185], v[122:125]
	v_mfma_f32_16x16x32_bf16 v[60:63], v[146:149], v[186:189], v[60:63]
	v_mfma_f32_16x16x32_bf16 v[60:63], v[150:153], v[190:193], v[60:63]
	v_mfma_f32_16x16x32_bf16 v[40:43], v[154:157], v[186:189], v[40:43]
	v_mfma_f32_16x16x32_bf16 v[40:43], v[158:161], v[190:193], v[40:43]
	v_mfma_f32_16x16x32_bf16 v[28:31], v[146:149], v[194:197], v[28:31]
	v_mfma_f32_16x16x32_bf16 v[28:31], v[150:153], v[200:203], v[28:31]
	v_mfma_f32_16x16x32_bf16 v[24:27], v[154:157], v[194:197], v[24:27]
	v_mfma_f32_16x16x32_bf16 v[24:27], v[158:161], v[200:203], v[24:27]
	v_mfma_f32_16x16x32_bf16 v[12:15], v[146:149], v[206:209], v[12:15]
	v_mfma_f32_16x16x32_bf16 v[12:15], v[150:153], v[210:213], v[12:15]
	v_mfma_f32_16x16x32_bf16 v[8:11], v[154:157], v[206:209], v[8:11]
	v_mfma_f32_16x16x32_bf16 v[8:11], v[158:161], v[210:213], v[8:11]
	s_setprio 0
	s_setprio 1
	v_mfma_f32_16x16x32_bf16 v[118:121], v[162:165], v[178:181], v[118:121]
	v_mfma_f32_16x16x32_bf16 v[118:121], v[166:169], v[182:185], v[118:121]
	v_mfma_f32_16x16x32_bf16 v[114:117], v[170:173], v[178:181], v[114:117]
	v_mfma_f32_16x16x32_bf16 v[114:117], v[174:177], v[182:185], v[114:117]
	v_mfma_f32_16x16x32_bf16 v[36:39], v[162:165], v[186:189], v[36:39]
	v_mfma_f32_16x16x32_bf16 v[36:39], v[166:169], v[190:193], v[36:39]
	v_mfma_f32_16x16x32_bf16 v[32:35], v[170:173], v[186:189], v[32:35]
	v_mfma_f32_16x16x32_bf16 v[32:35], v[174:177], v[190:193], v[32:35]
	v_mfma_f32_16x16x32_bf16 v[20:23], v[162:165], v[194:197], v[20:23]
	v_mfma_f32_16x16x32_bf16 v[20:23], v[166:169], v[200:203], v[20:23]
	v_mfma_f32_16x16x32_bf16 v[16:19], v[170:173], v[194:197], v[16:19]
	v_mfma_f32_16x16x32_bf16 v[16:19], v[174:177], v[200:203], v[16:19]
	v_mfma_f32_16x16x32_bf16 v[4:7], v[162:165], v[206:209], v[4:7]
	v_mfma_f32_16x16x32_bf16 v[0:3], v[170:173], v[206:209], v[0:3]
	s_setprio 2
	s_barrier
	v_mfma_f32_16x16x32_bf16 v[4:7], v[166:169], v[210:213], v[4:7]
	v_mfma_f32_16x16x32_bf16 v[0:3], v[174:177], v[210:213], v[0:3]
	s_setprio 0
	s_add_u32 s57, s57, 0x100
	s_addc_u32 s59, s59, 0
	s_cmp_ge_i32 vcc_lo, s53
	s_mov_b64 s[82:83], s[70:71]
	s_mov_b32 s72, vcc_lo
	s_cbranch_scc0 .LBB0_1523
